# stack6 + accumulators initialised by C=0 in the peeled first iteration (no 128 v_mov) + attention warm start without compiler vmcnt(0)
# speedup vs baseline: 1.0124x; 1.0124x over previous
; #define PG8_STAGE(bufoff, gbase) do { _Pragma("unroll") for (int _i = 0; _i < 2; ++_i) \
;         __builtin_amdgcn_global_load_lds((const unsigned*)((const char*)(gbase) + voffA[_i]), (LAS unsigned*)(lds + (bufoff) + ldsw + _i * 8192), 16, 0, 0); } while (0)
; #define PG8_LDA(dst, b, h) do { _Pragma("unroll") for (int m = 0; m < 4; ++m) _Pragma("unroll") for (int k = 0; k < 2; ++k) dst[m][k] = *(const LAS h16x8*)(lds + PG8_SA(b, h) + aoff + m * 2048 + k * 1024); } while (0)
; #define PG8_LDB(dst, b, h) do { _Pragma("unroll") for (int n = 0; n < 2; ++n) _Pragma("unroll") for (int k = 0; k < 2; ++k) dst[n][k] = *(const LAS h16x8*)(lds + PG8_SB(b, h) + boff + n * 2048 + k * 1024); } while (0)
; #define PG8_LDA1(dst, b) do { if constexpr (!HALFM) PG8_LDA(dst, b, 1); } while (0)
; #define PG8_MMA1(At, B0, B1) do { if constexpr (!HALFM) { PG8_MMA(1, 0, At, B0); PG8_MMA(1, 1, At, B1); } } while (0)
; #define PG8_WAIT_V(n) asm volatile("s_waitcnt vmcnt(" #n ")" ::: "memory")
; #define PG8_WAIT_L(n) asm volatile("s_waitcnt lgkmcnt(" #n ")" ::: "memory")
; #define PG8_BAR __builtin_amdgcn_s_barrier()
; #define PG8_SCHED __builtin_amdgcn_sched_barrier(0)
; template <class Epi, bool ALIGN_EPI, bool SP2, bool BF = false, bool HALFM = false, class Order = StaticOrder>
; __device__ __forceinline__ void gemm_phase(LAS unsigned char* lds, const int tid, const Gemm g, const Order& S, const Epi& E, const bool dry = false) {
;     ...
;             if constexpr (SP2) {
;             PG8_LDB(B0, 0, 0); PG8_LDB(B1, 0, 1); PG8_SCHED; PG8_LDA(At, 0, 0); PG8_STAGE(PG8_SA(1, 1), a1 + hstep);
;             PG8_WAIT_V(8); PG8_WAIT_L(0); PG8_BAR; PG8_MMA(0, 0, At, B0); PG8_MMA(0, 1, At, B1); PG8_BAR; PG8_SCHED;
;             PG8_LDA1(At, 0); PG8_STAGE(PG8_SB(0, 0), b2); PG8_STAGE(PG8_SB(0, 1), b2 + hstep); PG8_STAGE(PG8_SA(0, 0), a2);
;             PG8_WAIT_V(8); PG8_WAIT_L(0); PG8_BAR; PG8_MMA1(At, B0, B1); PG8_BAR; PG8_SCHED;
.Lin_peel:
	v_add_u32_e32 v144, s46, v198
	v_add_u32_e32 v160, s49, v198
	ds_read_b128 v[132:135], v144
	ds_read_b128 v[136:139], v144 offset:1024
	ds_read_b128 v[140:143], v144 offset:2048
	ds_read_b128 v[144:147], v144 offset:3072
	ds_read_b128 v[148:151], v160
	ds_read_b128 v[152:155], v160 offset:1024
	ds_read_b128 v[156:159], v160 offset:2048
	ds_read_b128 v[160:163], v160 offset:3072
	s_add_u32 s38, s36, 0xfffc0080
	s_addc_u32 s39, s37, -1
	s_cmp_eq_u32 s21, 12
	s_cselect_b32 s43, s3, s39
	s_cselect_b32 s42, s5, s38
	s_cselect_b32 s39, s8, s19
	s_cselect_b32 s38, s9, s11
	v_lshl_add_u64 v[194:195], s[36:37], 0, v[168:169]
	s_add_i32 m0, s52, 0xc000
	ds_read_b128 v[170:173], v199
	ds_read_b128 v[174:177], v199 offset:1024
	ds_read_b128 v[178:181], v199 offset:2048
	ds_read_b128 v[182:185], v199 offset:3072
	ds_read_b128 v[186:189], v199 offset:4096
	ds_read_b128 v[190:193], v199 offset:5120
	ds_read_b128 v[200:203], v199 offset:6144
	ds_read_b128 v[204:207], v199 offset:7168
	s_nop 0
	v_lshl_add_u64 v[194:195], s[36:37], 0, v[166:167]
	s_add_i32 m0, s52, 0xe000
	s_nop 0
	s_nop 0
	s_nop 0
	s_waitcnt lgkmcnt(0)
	s_barrier
	s_waitcnt lgkmcnt(0)
	v_mfma_f32_16x16x32_f16 v[70:73], v[132:135], v[170:173], 0
	v_mfma_f32_16x16x32_f16 v[66:69], v[140:143], v[170:173], 0
	v_mfma_f32_16x16x32_f16 v[50:53], v[132:135], v[178:181], 0
	v_mfma_f32_16x16x32_f16 v[46:49], v[140:143], v[178:181], 0
	v_mfma_f32_16x16x32_f16 v[54:57], v[132:135], v[186:189], 0
	v_mfma_f32_16x16x32_f16 v[42:45], v[140:143], v[186:189], 0
	v_mfma_f32_16x16x32_f16 v[38:41], v[132:135], v[200:203], 0
	v_mfma_f32_16x16x32_f16 v[34:37], v[140:143], v[200:203], 0
	v_mfma_f32_16x16x32_f16 v[70:73], v[136:139], v[174:177], v[70:73]
	v_mfma_f32_16x16x32_f16 v[66:69], v[144:147], v[174:177], v[66:69]
	v_mfma_f32_16x16x32_f16 v[50:53], v[136:139], v[182:185], v[50:53]
	v_mfma_f32_16x16x32_f16 v[46:49], v[144:147], v[182:185], v[46:49]
	v_mfma_f32_16x16x32_f16 v[54:57], v[136:139], v[190:193], v[54:57]
	v_mfma_f32_16x16x32_f16 v[42:45], v[144:147], v[190:193], v[42:45]
	v_mfma_f32_16x16x32_f16 v[38:41], v[136:139], v[204:207], v[38:41]
	v_mfma_f32_16x16x32_f16 v[34:37], v[144:147], v[204:207], v[34:37]
	v_mfma_f32_16x16x32_f16 v[126:129], v[148:151], v[170:173], 0
	v_mfma_f32_16x16x32_f16 v[122:125], v[156:159], v[170:173], 0
	v_mfma_f32_16x16x32_f16 v[118:121], v[148:151], v[178:181], 0
	v_mfma_f32_16x16x32_f16 v[114:117], v[156:159], v[178:181], 0
	v_mfma_f32_16x16x32_f16 v[110:113], v[148:151], v[186:189], 0
	v_mfma_f32_16x16x32_f16 v[106:109], v[156:159], v[186:189], 0
	v_mfma_f32_16x16x32_f16 v[102:105], v[148:151], v[200:203], 0
	v_mfma_f32_16x16x32_f16 v[98:101], v[156:159], v[200:203], 0
	v_mfma_f32_16x16x32_f16 v[126:129], v[152:155], v[174:177], v[126:129]
	v_mfma_f32_16x16x32_f16 v[122:125], v[160:163], v[174:177], v[122:125]
	v_mfma_f32_16x16x32_f16 v[118:121], v[152:155], v[182:185], v[118:121]
	v_mfma_f32_16x16x32_f16 v[114:117], v[160:163], v[182:185], v[114:117]
	v_mfma_f32_16x16x32_f16 v[110:113], v[152:155], v[190:193], v[110:113]
	v_mfma_f32_16x16x32_f16 v[106:109], v[160:163], v[190:193], v[106:109]
	v_mfma_f32_16x16x32_f16 v[102:105], v[152:155], v[204:207], v[102:105]
	v_mfma_f32_16x16x32_f16 v[98:101], v[160:163], v[204:207], v[98:101]
	s_barrier
	s_mov_b32 m0, s47
	v_lshl_add_u64 v[194:195], s[38:39], 0, v[0:1]
	s_add_u32 vcc_lo, s38, 0x40000
	ds_read_b128 v[170:173], v199 offset:16384
	ds_read_b128 v[174:177], v199 offset:17408
	ds_read_b128 v[178:181], v199 offset:18432
	ds_read_b128 v[182:185], v199 offset:19456
	ds_read_b128 v[186:189], v199 offset:20480
	ds_read_b128 v[190:193], v199 offset:21504
	ds_read_b128 v[200:203], v199 offset:22528
	ds_read_b128 v[204:207], v199 offset:23552
	global_load_lds_dwordx4 v[194:195], off
	v_lshl_add_u64 v[214:215], s[38:39], 0, v[164:165]
	s_mov_b32 m0, s48
	s_addc_u32 vcc_hi, s39, 0
	global_load_lds_dwordx4 v[214:215], off
	v_lshl_add_u64 v[216:217], vcc, 0, v[0:1]
	s_mov_b32 m0, s50
	v_lshl_add_u64 v[218:219], s[42:43], 0, v[164:165]
	global_load_lds_dwordx4 v[216:217], off
	v_lshl_add_u64 v[216:217], vcc, 0, v[164:165]
	s_mov_b32 m0, s51
	s_nop 0
	global_load_lds_dwordx4 v[216:217], off
	v_lshl_add_u64 v[216:217], s[42:43], 0, v[0:1]
	s_mov_b32 m0, s52
	s_nop 0
	global_load_lds_dwordx4 v[216:217], off
	s_mov_b32 m0, s53
	s_nop 0
	global_load_lds_dwordx4 v[218:219], off
	s_nop 0
	s_waitcnt lgkmcnt(0)
	s_barrier
; #define PG8_STAGE(bufoff, gbase) do { _Pragma("unroll") for (int _i = 0; _i < 2; ++_i) \
;         __builtin_amdgcn_global_load_lds((const unsigned*)((const char*)(gbase) + voffA[_i]), (LAS unsigned*)(lds + (bufoff) + ldsw + _i * 8192), 16, 0, 0); } while (0)
; #define PG8_LDA(dst, b, h) do { _Pragma("unroll") for (int m = 0; m < 4; ++m) _Pragma("unroll") for (int k = 0; k < 2; ++k) dst[m][k] = *(const LAS h16x8*)(lds + PG8_SA(b, h) + aoff + m * 2048 + k * 1024); } while (0)
; #define PG8_LDB(dst, b, h) do { _Pragma("unroll") for (int n = 0; n < 2; ++n) _Pragma("unroll") for (int k = 0; k < 2; ++k) dst[n][k] = *(const LAS h16x8*)(lds + PG8_SB(b, h) + boff + n * 2048 + k * 1024); } while (0)
; #define PG8_MMA1(At, B0, B1) do { if constexpr (!HALFM) { PG8_MMA(1, 0, At, B0); PG8_MMA(1, 1, At, B1); } } while (0)
; #define PG8_WAIT_V(n) asm volatile("s_waitcnt vmcnt(" #n ")" ::: "memory")
; #define PG8_WAIT_L(n) asm volatile("s_waitcnt lgkmcnt(" #n ")" ::: "memory")
; #define PG8_BAR __builtin_amdgcn_s_barrier()
; #define PG8_SCHED __builtin_amdgcn_sched_barrier(0)
; template <class Epi, bool ALIGN_EPI, bool SP2, bool BF = false, bool HALFM = false, class Order = StaticOrder>
; __device__ __forceinline__ void gemm_phase(LAS unsigned char* lds, const int tid, const Gemm g, const Order& S, const Epi& E, const bool dry = false) {
;     ...
;             PG8_WAIT_V(8); PG8_WAIT_L(0); PG8_BAR; PG8_MMA1(At, B0, B1); PG8_BAR; PG8_SCHED;
;             PG8_LDB(B0, 1, 0); PG8_LDB(B1, 1, 1); PG8_SCHED; PG8_LDA(At, 1, 0); PG8_STAGE(PG8_SA(0, 1), a2 + hstep);
;             PG8_WAIT_V(8); PG8_WAIT_L(0); PG8_BAR; PG8_MMA(0, 0, At, B0); PG8_MMA(0, 1, At, B1); PG8_BAR; PG8_SCHED;
	s_waitcnt lgkmcnt(0)
	v_mfma_f32_16x16x32_f16 v[30:33], v[132:135], v[170:173], 0
	v_mfma_f32_16x16x32_f16 v[26:29], v[140:143], v[170:173], 0
	v_mfma_f32_16x16x32_f16 v[22:25], v[132:135], v[178:181], 0
	v_mfma_f32_16x16x32_f16 v[18:21], v[140:143], v[178:181], 0
	v_mfma_f32_16x16x32_f16 v[14:17], v[132:135], v[186:189], 0
	v_mfma_f32_16x16x32_f16 v[10:13], v[140:143], v[186:189], 0
	v_mfma_f32_16x16x32_f16 v[6:9], v[132:135], v[200:203], 0
	v_mfma_f32_16x16x32_f16 v[2:5], v[140:143], v[200:203], 0
	v_mfma_f32_16x16x32_f16 v[30:33], v[136:139], v[174:177], v[30:33]
	v_mfma_f32_16x16x32_f16 v[26:29], v[144:147], v[174:177], v[26:29]
	v_mfma_f32_16x16x32_f16 v[22:25], v[136:139], v[182:185], v[22:25]
	v_mfma_f32_16x16x32_f16 v[18:21], v[144:147], v[182:185], v[18:21]
	v_mfma_f32_16x16x32_f16 v[14:17], v[136:139], v[190:193], v[14:17]
	v_mfma_f32_16x16x32_f16 v[10:13], v[144:147], v[190:193], v[10:13]
	v_mfma_f32_16x16x32_f16 v[6:9], v[136:139], v[204:207], v[6:9]
	v_mfma_f32_16x16x32_f16 v[2:5], v[144:147], v[204:207], v[2:5]
	v_mfma_f32_16x16x32_f16 v[94:97], v[148:151], v[170:173], 0
	v_mfma_f32_16x16x32_f16 v[90:93], v[156:159], v[170:173], 0
	v_mfma_f32_16x16x32_f16 v[86:89], v[148:151], v[178:181], 0
	v_mfma_f32_16x16x32_f16 v[82:85], v[156:159], v[178:181], 0
	v_mfma_f32_16x16x32_f16 v[78:81], v[148:151], v[186:189], 0
	v_mfma_f32_16x16x32_f16 v[74:77], v[156:159], v[186:189], 0
	v_mfma_f32_16x16x32_f16 v[62:65], v[148:151], v[200:203], 0
	v_mfma_f32_16x16x32_f16 v[58:61], v[156:159], v[200:203], 0
	v_mfma_f32_16x16x32_f16 v[94:97], v[152:155], v[174:177], v[94:97]
	v_mfma_f32_16x16x32_f16 v[90:93], v[160:163], v[174:177], v[90:93]
	v_mfma_f32_16x16x32_f16 v[86:89], v[152:155], v[182:185], v[86:89]
	v_mfma_f32_16x16x32_f16 v[82:85], v[160:163], v[182:185], v[82:85]
	v_mfma_f32_16x16x32_f16 v[78:81], v[152:155], v[190:193], v[78:81]
	v_mfma_f32_16x16x32_f16 v[74:77], v[160:163], v[190:193], v[74:77]
	v_mfma_f32_16x16x32_f16 v[62:65], v[152:155], v[204:207], v[62:65]
	v_mfma_f32_16x16x32_f16 v[58:61], v[160:163], v[204:207], v[58:61]
	s_barrier
	v_add_u32_e32 v144, s79, v198
	v_add_u32_e32 v160, s84, v198
	ds_read_b128 v[132:135], v144
	ds_read_b128 v[136:139], v144 offset:1024
	ds_read_b128 v[140:143], v144 offset:2048
	ds_read_b128 v[144:147], v144 offset:3072
	ds_read_b128 v[148:151], v160
	ds_read_b128 v[152:155], v160 offset:1024
	ds_read_b128 v[156:159], v160 offset:2048
	ds_read_b128 v[160:163], v160 offset:3072
	s_add_u32 s42, s42, 0x40000
	s_addc_u32 s43, s43, 0
	s_mov_b32 m0, s54
	v_lshl_add_u64 v[220:221], s[42:43], 0, v[0:1]
	ds_read_b128 v[170:173], v199 offset:32768
	ds_read_b128 v[174:177], v199 offset:33792
	ds_read_b128 v[178:181], v199 offset:34816
	ds_read_b128 v[182:185], v199 offset:35840
	ds_read_b128 v[186:189], v199 offset:36864
	ds_read_b128 v[190:193], v199 offset:37888
	ds_read_b128 v[200:203], v199 offset:38912
	ds_read_b128 v[204:207], v199 offset:39936
	global_load_lds_dwordx4 v[220:221], off
	v_lshl_add_u64 v[220:221], s[42:43], 0, v[164:165]
	s_mov_b32 m0, s55
	s_nop 0
	global_load_lds_dwordx4 v[220:221], off
	s_nop 0
	s_waitcnt lgkmcnt(0)
	s_barrier
	s_waitcnt lgkmcnt(0)
	v_mfma_f32_16x16x32_f16 v[70:73], v[132:135], v[170:173], v[70:73]
	v_mfma_f32_16x16x32_f16 v[66:69], v[140:143], v[170:173], v[66:69]
	v_mfma_f32_16x16x32_f16 v[50:53], v[132:135], v[178:181], v[50:53]
	v_mfma_f32_16x16x32_f16 v[46:49], v[140:143], v[178:181], v[46:49]
	v_mfma_f32_16x16x32_f16 v[54:57], v[132:135], v[186:189], v[54:57]
	v_mfma_f32_16x16x32_f16 v[42:45], v[140:143], v[186:189], v[42:45]
	v_mfma_f32_16x16x32_f16 v[38:41], v[132:135], v[200:203], v[38:41]
	v_mfma_f32_16x16x32_f16 v[34:37], v[140:143], v[200:203], v[34:37]
	v_mfma_f32_16x16x32_f16 v[70:73], v[136:139], v[174:177], v[70:73]
	v_mfma_f32_16x16x32_f16 v[66:69], v[144:147], v[174:177], v[66:69]
	v_mfma_f32_16x16x32_f16 v[50:53], v[136:139], v[182:185], v[50:53]
	v_mfma_f32_16x16x32_f16 v[46:49], v[144:147], v[182:185], v[46:49]
	v_mfma_f32_16x16x32_f16 v[54:57], v[136:139], v[190:193], v[54:57]
	v_mfma_f32_16x16x32_f16 v[42:45], v[144:147], v[190:193], v[42:45]
	v_mfma_f32_16x16x32_f16 v[38:41], v[136:139], v[204:207], v[38:41]
	v_mfma_f32_16x16x32_f16 v[34:37], v[144:147], v[204:207], v[34:37]
	v_mfma_f32_16x16x32_f16 v[126:129], v[148:151], v[170:173], v[126:129]
	v_mfma_f32_16x16x32_f16 v[122:125], v[156:159], v[170:173], v[122:125]
	v_mfma_f32_16x16x32_f16 v[118:121], v[148:151], v[178:181], v[118:121]
	v_mfma_f32_16x16x32_f16 v[114:117], v[156:159], v[178:181], v[114:117]
	v_mfma_f32_16x16x32_f16 v[110:113], v[148:151], v[186:189], v[110:113]
	v_mfma_f32_16x16x32_f16 v[106:109], v[156:159], v[186:189], v[106:109]
	v_mfma_f32_16x16x32_f16 v[102:105], v[148:151], v[200:203], v[102:105]
	v_mfma_f32_16x16x32_f16 v[98:101], v[156:159], v[200:203], v[98:101]
	v_mfma_f32_16x16x32_f16 v[126:129], v[152:155], v[174:177], v[126:129]
	v_mfma_f32_16x16x32_f16 v[122:125], v[160:163], v[174:177], v[122:125]
	v_mfma_f32_16x16x32_f16 v[118:121], v[152:155], v[182:185], v[118:121]
	v_mfma_f32_16x16x32_f16 v[114:117], v[160:163], v[182:185], v[114:117]
	v_mfma_f32_16x16x32_f16 v[110:113], v[152:155], v[190:193], v[110:113]
	v_mfma_f32_16x16x32_f16 v[106:109], v[160:163], v[190:193], v[106:109]
	v_mfma_f32_16x16x32_f16 v[102:105], v[152:155], v[204:207], v[102:105]
	v_mfma_f32_16x16x32_f16 v[98:101], v[160:163], v[204:207], v[98:101]
	s_barrier
	s_branch .Lin_seg4

; template <class Epi, bool ALIGN_EPI, bool SP2, bool BF = false, bool HALFM = false, class Order = StaticOrder>
; __device__ __forceinline__ void gemm_phase(LAS unsigned char* lds, const int tid, const Gemm g, const Order& S, const Epi& E, const bool dry = false) {
;     ...
;         for (int a = 0; a < 2; ++a)
; #pragma unroll
;             for (int b = 0; b < 2; ++b)
; #pragma unroll
;                 for (int m = 0; m < 4; ++m)
; #pragma unroll
;                     for (int n = 0; n < 2; ++n) acc[a][b][m][n] = (f32x4){0.f, 0.f, 0.f, 0.f};
.Lin_wd:
	s_mov_b32 s21, -2
	s_cmp_lg_u32 s100, 0
	s_cbranch_scc1 .Lin_peel
	v_mov_b32_e32 v58, 0
	v_mov_b32_e32 v59, v58
	v_mov_b32_e32 v60, v58
	v_mov_b32_e32 v61, v58
	v_mov_b32_e32 v62, v58
	v_mov_b32_e32 v63, v58
	v_mov_b32_e32 v64, v58
	v_mov_b32_e32 v65, v58
	v_mov_b32_e32 v74, v58
	v_mov_b32_e32 v75, v58
	v_mov_b32_e32 v76, v58
	v_mov_b32_e32 v77, v58
	v_mov_b32_e32 v78, v58
	v_mov_b32_e32 v79, v58
	v_mov_b32_e32 v80, v58
	v_mov_b32_e32 v81, v58
	v_mov_b32_e32 v82, v58
	v_mov_b32_e32 v83, v58
	v_mov_b32_e32 v84, v58
	v_mov_b32_e32 v85, v58
	v_mov_b32_e32 v86, v58
	v_mov_b32_e32 v87, v58
	v_mov_b32_e32 v88, v58
	v_mov_b32_e32 v89, v58
	v_mov_b32_e32 v90, v58
	v_mov_b32_e32 v91, v58
	v_mov_b32_e32 v92, v58
	v_mov_b32_e32 v93, v58
	v_mov_b32_e32 v94, v58
	v_mov_b32_e32 v95, v58
	v_mov_b32_e32 v96, v58
	v_mov_b32_e32 v97, v58
	v_mov_b32_e32 v2, v58
	v_mov_b32_e32 v3, v58
	v_mov_b32_e32 v4, v58
	v_mov_b32_e32 v5, v58
	v_mov_b32_e32 v6, v58
	v_mov_b32_e32 v7, v58
	v_mov_b32_e32 v8, v58
	v_mov_b32_e32 v9, v58
	v_mov_b32_e32 v10, v58
	v_mov_b32_e32 v11, v58
	v_mov_b32_e32 v12, v58
	v_mov_b32_e32 v13, v58
	v_mov_b32_e32 v14, v58
	v_mov_b32_e32 v15, v58
	v_mov_b32_e32 v16, v58
	v_mov_b32_e32 v17, v58
	v_mov_b32_e32 v18, v58
	v_mov_b32_e32 v19, v58
	v_mov_b32_e32 v20, v58
	v_mov_b32_e32 v21, v58
	v_mov_b32_e32 v22, v58
	v_mov_b32_e32 v23, v58
	v_mov_b32_e32 v24, v58
	v_mov_b32_e32 v25, v58
	v_mov_b32_e32 v26, v58
	v_mov_b32_e32 v27, v58
	v_mov_b32_e32 v28, v58
	v_mov_b32_e32 v29, v58
	v_mov_b32_e32 v30, v58
	v_mov_b32_e32 v31, v58
	v_mov_b32_e32 v32, v58
	v_mov_b32_e32 v33, v58
	v_mov_b32_e32 v98, v58
	v_mov_b32_e32 v99, v58
	v_mov_b32_e32 v100, v58
	v_mov_b32_e32 v101, v58
	v_mov_b32_e32 v102, v58
	v_mov_b32_e32 v103, v58
	v_mov_b32_e32 v104, v58
	v_mov_b32_e32 v105, v58
	v_mov_b32_e32 v106, v58
	v_mov_b32_e32 v107, v58
	v_mov_b32_e32 v108, v58
	v_mov_b32_e32 v109, v58
	v_mov_b32_e32 v110, v58
	v_mov_b32_e32 v111, v58
	v_mov_b32_e32 v112, v58
	v_mov_b32_e32 v113, v58
	v_mov_b32_e32 v114, v58
	v_mov_b32_e32 v115, v58
	v_mov_b32_e32 v116, v58
	v_mov_b32_e32 v117, v58
	v_mov_b32_e32 v118, v58
	v_mov_b32_e32 v119, v58
	v_mov_b32_e32 v120, v58
	v_mov_b32_e32 v121, v58
	v_mov_b32_e32 v122, v58
	v_mov_b32_e32 v123, v58
	v_mov_b32_e32 v124, v58
	v_mov_b32_e32 v125, v58
	v_mov_b32_e32 v126, v58
	v_mov_b32_e32 v127, v58
	v_mov_b32_e32 v128, v58
	v_mov_b32_e32 v129, v58
	v_mov_b32_e32 v34, v58
	v_mov_b32_e32 v35, v58
	v_mov_b32_e32 v36, v58
	v_mov_b32_e32 v37, v58
	v_mov_b32_e32 v38, v58
	v_mov_b32_e32 v39, v58
	v_mov_b32_e32 v40, v58
	v_mov_b32_e32 v41, v58
	v_mov_b32_e32 v42, v58
	v_mov_b32_e32 v43, v58
	v_mov_b32_e32 v44, v58
	v_mov_b32_e32 v45, v58
	v_mov_b32_e32 v54, v58
	v_mov_b32_e32 v55, v58
	v_mov_b32_e32 v56, v58
	v_mov_b32_e32 v57, v58
	v_mov_b32_e32 v46, v58
	v_mov_b32_e32 v47, v58
	v_mov_b32_e32 v48, v58
	v_mov_b32_e32 v49, v58
	v_mov_b32_e32 v50, v58
	v_mov_b32_e32 v51, v58
	v_mov_b32_e32 v52, v58
	v_mov_b32_e32 v53, v58
	v_mov_b32_e32 v66, v58
	v_mov_b32_e32 v67, v58
	v_mov_b32_e32 v68, v58
	v_mov_b32_e32 v69, v58
	v_mov_b32_e32 v70, v58
	v_mov_b32_e32 v71, v58
	v_mov_b32_e32 v72, v58
	v_mov_b32_e32 v73, v58
